# prep3a 64-lane sums via DPP + permlane swaps instead of six ds_bpermute round trips each
# baseline (speedup 1.0000x reference)
.LBB0_693:
	v_readlane_b32 s40, v254, 24
	s_andn2_b64 vcc, exec, s[0:1]
	v_readlane_b32 s41, v254, 25
	s_cbranch_vccnz .LBB0_786
	s_waitcnt lgkmcnt(0)
	v_readlane_b32 s2, v254, 8
	v_readlane_b32 s3, v254, 9
	s_mov_b64 s[0:1], -1
	s_and_b64 vcc, exec, s[2:3]
	s_movk_i32 s19, 0xfff
	s_cbranch_vccz .LBB0_767
	v_readlane_b32 s2, v254, 12
	v_readlane_b32 s3, v254, 13
	v_readlane_b32 s50, v254, 22
	s_and_b64 vcc, exec, s[2:3]
	s_movk_i32 s17, 0x4000
	s_mov_b32 s18, 0xbfb8aa3b
	s_movk_i32 s27, 0x1a00
	s_mov_b32 s40, 0x40000
	s_mov_b32 s41, 0x3ffff
	s_mov_b32 s43, 0x100000
	s_mov_b32 s44, 0xfffff
	s_mov_b32 s48, 0x3f317217
	s_mov_b32 s49, 0x7f800000
	v_readlane_b32 s51, v254, 23
	s_cbranch_vccz .LBB0_756
	v_readlane_b32 s2, v254, 14
	v_readlane_b32 s3, v254, 15
	s_and_b64 vcc, exec, s[2:3]
	s_mov_b32 s16, 0xffff
	s_mov_b32 s42, 0x7ffff
	s_mov_b32 s47, 0x7060302
	s_cbranch_vccz .LBB0_720
	v_mov_b32_e32 v1, v0
	v_mov_b32_e32 v2, v0
	s_mov_b32 s0, s87
	v_ashrrev_i32_e32 v2, 6, v2
	s_nop 0
	v_lshl_add_u32 v4, s0, 3, v2
	s_movk_i32 s0, 0x2000
	v_cmp_gt_i32_e32 vcc, s0, v4
	s_and_saveexec_b64 s[0:1], vcc
	s_cbranch_execz .LBB0_711
	v_and_b32_e32 v6, 63, v1
	v_and_b32_e32 v1, 64, v223
	v_add_u32_e32 v5, 64, v1
	v_xor_b32_e32 v1, 32, v223
	v_cmp_lt_i32_e32 vcc, v1, v5
	v_xor_b32_e32 v7, 16, v223
	v_xor_b32_e32 v12, 8, v223
	v_cndmask_b32_e32 v1, v223, v1, vcc
	v_cmp_lt_i32_e32 vcc, v7, v5
	s_load_dword s2, s[20:21], 0x0
	s_load_dwordx2 s[6:7], s[30:31], 0x130
	s_load_dwordx2 s[8:9], s[30:31], 0x148
	v_cndmask_b32_e32 v7, v223, v7, vcc
	v_cmp_lt_i32_e32 vcc, v12, v5
	v_lshlrev_b32_e32 v14, 2, v6
	v_mov_b32_e32 v15, v3
	v_cndmask_b32_e32 v12, v223, v12, vcc
	v_lshlrev_b32_e32 v34, 2, v12
	v_xor_b32_e32 v12, 4, v223
	v_cmp_lt_i32_e32 vcc, v12, v5
	v_lshlrev_b32_e32 v2, 1, v6
	v_lshl_add_u64 v[8:9], s[36:37], 0, v[2:3]
	v_cndmask_b32_e32 v12, v223, v12, vcc
	v_lshlrev_b32_e32 v35, 2, v12
	v_xor_b32_e32 v12, 2, v223
	v_cmp_lt_i32_e32 vcc, v12, v5
	v_lshl_add_u64 v[10:11], s[76:77], 0, v[2:3]
	v_cmp_gt_u32_e64 s[4:5], 32, v6
	v_cndmask_b32_e32 v12, v223, v12, vcc
	v_lshlrev_b32_e32 v37, 2, v12
	v_xor_b32_e32 v12, 1, v223
	v_cmp_lt_i32_e32 vcc, v12, v5
	s_waitcnt lgkmcnt(0)
	s_lshl_b32 s2, s2, 3
	v_lshlrev_b32_e32 v1, 2, v1
	v_cndmask_b32_e32 v5, v223, v12, vcc
	v_lshl_add_u64 v[12:13], s[6:7], 0, v[14:15]
	v_readlane_b32 s6, v254, 20
	v_readlane_b32 s7, v254, 21
	v_lshlrev_b32_e32 v7, 2, v7
	v_lshlrev_b32_e32 v38, 2, v5
	v_lshl_add_u64 v[14:15], s[8:9], 0, v[14:15]
	v_lshl_add_u64 v[16:17], s[34:35], 0, v[2:3]
	v_lshl_add_u64 v[18:19], s[6:7], 0, v[2:3]
	s_mov_b64 s[6:7], 0
	s_cmp_eq_u32 s2, 0x800
	s_cbranch_scc0 .LBB0_700
	v_readfirstlane_b32 s3, v4
	s_cmp_lt_u32 s3, 0x800
	s_cbranch_scc0 .LBB0_700
	s_load_dwordx2 s[10:11], s[30:31], 0x170
	global_load_dword v124, v[12:13], off
	global_load_dword v125, v[12:13], off offset:256
	global_load_dword v126, v[12:13], off offset:512
	global_load_dword v127, v[12:13], off offset:768
	global_load_dword v128, v[12:13], off offset:1024
	global_load_dword v129, v[12:13], off offset:1280
	global_load_dword v130, v[14:15], off
	global_load_dword v131, v[14:15], off offset:256
	global_load_dword v132, v[14:15], off offset:512
	global_load_dword v133, v[14:15], off offset:768
	v_mov_b32_e32 v134, v4
	s_movk_i32 s3, 0x600
	v_mad_i64_i32 v[136:137], s[8:9], v134, s3, v[16:17]
	v_mad_i64_i32 v[142:143], s[8:9], v134, s3, v[18:19]
	global_load_ushort v80, v[136:137], off
	global_load_ushort v81, v[136:137], off offset:128
	global_load_ushort v82, v[136:137], off offset:256
	global_load_ushort v83, v[136:137], off offset:384
	global_load_ushort v84, v[136:137], off offset:512
	global_load_ushort v85, v[136:137], off offset:640
	global_load_ushort v86, v[136:137], off offset:768
	global_load_ushort v87, v[136:137], off offset:896
	global_load_ushort v88, v[136:137], off offset:1024
	global_load_ushort v89, v[136:137], off offset:1152
	global_load_ushort v90, v[136:137], off offset:1280
	global_load_ushort v91, v[142:143], off
	global_load_ushort v92, v[142:143], off offset:128
	global_load_ushort v93, v[142:143], off offset:256
	global_load_ushort v94, v[142:143], off offset:384
	global_load_ushort v95, v[142:143], off offset:512
	global_load_ushort v96, v[142:143], off offset:640
	global_load_ushort v97, v[142:143], off offset:768
	global_load_ushort v98, v[142:143], off offset:896
	global_load_ushort v99, v[142:143], off offset:1024
	global_load_ushort v100, v[142:143], off offset:1152
	global_load_ushort v101, v[142:143], off offset:1280
	v_add_u32_e32 v135, 0x800, v4
	s_movk_i32 s3, 0x600
	v_mad_i64_i32 v[138:139], s[8:9], v135, s3, v[16:17]
	v_mad_i64_i32 v[144:145], s[8:9], v135, s3, v[18:19]
	global_load_ushort v102, v[138:139], off
	global_load_ushort v103, v[138:139], off offset:128
	global_load_ushort v104, v[138:139], off offset:256
	global_load_ushort v105, v[138:139], off offset:384
	global_load_ushort v106, v[138:139], off offset:512
	global_load_ushort v107, v[138:139], off offset:640
	global_load_ushort v108, v[138:139], off offset:768
	global_load_ushort v109, v[138:139], off offset:896
	global_load_ushort v110, v[138:139], off offset:1024
	global_load_ushort v111, v[138:139], off offset:1152
	global_load_ushort v112, v[138:139], off offset:1280
	global_load_ushort v113, v[144:145], off
	global_load_ushort v114, v[144:145], off offset:128
	global_load_ushort v115, v[144:145], off offset:256
	global_load_ushort v116, v[144:145], off offset:384
	global_load_ushort v117, v[144:145], off offset:512
	global_load_ushort v118, v[144:145], off offset:640
	global_load_ushort v119, v[144:145], off offset:768
	global_load_ushort v120, v[144:145], off offset:896
	global_load_ushort v121, v[144:145], off offset:1024
	global_load_ushort v122, v[144:145], off offset:1152
	global_load_ushort v123, v[144:145], off offset:1280
	s_waitcnt vmcnt(0)
	v_add_u32_e32 v248, 0x1000, v4
	s_movk_i32 s3, 0x600
	v_mad_i64_i32 v[250:251], s[8:9], v248, s3, v[16:17]
	v_mad_i64_i32 v[152:153], s[8:9], v248, s3, v[18:19]
	global_load_ushort v188, v[250:251], off
	global_load_ushort v189, v[250:251], off offset:128
	global_load_ushort v190, v[250:251], off offset:256
	global_load_ushort v191, v[250:251], off offset:384
	global_load_ushort v192, v[250:251], off offset:512
	global_load_ushort v193, v[250:251], off offset:640
	global_load_ushort v194, v[250:251], off offset:768
	global_load_ushort v195, v[250:251], off offset:896
	global_load_ushort v196, v[250:251], off offset:1024
	global_load_ushort v197, v[250:251], off offset:1152
	global_load_ushort v198, v[250:251], off offset:1280
	global_load_ushort v199, v[152:153], off
	global_load_ushort v200, v[152:153], off offset:128
	global_load_ushort v201, v[152:153], off offset:256
	global_load_ushort v202, v[152:153], off offset:384
	global_load_ushort v203, v[152:153], off offset:512
	global_load_ushort v204, v[152:153], off offset:640
	global_load_ushort v205, v[152:153], off offset:768
	global_load_ushort v206, v[152:153], off offset:896
	global_load_ushort v207, v[152:153], off offset:1024
	global_load_ushort v208, v[152:153], off offset:1152
	global_load_ushort v209, v[152:153], off offset:1280
	v_add_u32_e32 v249, 0x1800, v4
	s_movk_i32 s3, 0x600
	v_mad_i64_i32 v[252:253], s[8:9], v249, s3, v[16:17]
	v_mad_i64_i32 v[154:155], s[8:9], v249, s3, v[18:19]
	global_load_ushort v210, v[252:253], off
	global_load_ushort v211, v[252:253], off offset:128
	global_load_ushort v212, v[252:253], off offset:256
	global_load_ushort v213, v[252:253], off offset:384
	global_load_ushort v214, v[252:253], off offset:512
	global_load_ushort v215, v[252:253], off offset:640
	global_load_ushort v216, v[252:253], off offset:768
	global_load_ushort v217, v[252:253], off offset:896
	global_load_ushort v234, v[252:253], off offset:1024
	global_load_ushort v235, v[252:253], off offset:1152
	global_load_ushort v236, v[252:253], off offset:1280
	global_load_ushort v237, v[154:155], off
	global_load_ushort v238, v[154:155], off offset:128
	global_load_ushort v239, v[154:155], off offset:256
	global_load_ushort v240, v[154:155], off offset:384
	global_load_ushort v241, v[154:155], off offset:512
	global_load_ushort v242, v[154:155], off offset:640
	global_load_ushort v243, v[154:155], off offset:768
	global_load_ushort v244, v[154:155], off offset:896
	global_load_ushort v245, v[154:155], off offset:1024
	global_load_ushort v246, v[154:155], off offset:1152
	global_load_ushort v247, v[154:155], off offset:1280
	v_lshlrev_b32_e32 v80, 16, v80
	v_lshlrev_b32_e32 v91, 16, v91
	v_add_f32_e32 v80, v80, v91
	v_lshlrev_b32_e32 v81, 16, v81
	v_lshlrev_b32_e32 v92, 16, v92
	v_add_f32_e32 v81, v81, v92
	v_lshlrev_b32_e32 v82, 16, v82
	v_lshlrev_b32_e32 v93, 16, v93
	v_add_f32_e32 v82, v82, v93
	v_lshlrev_b32_e32 v83, 16, v83
	v_lshlrev_b32_e32 v94, 16, v94
	v_add_f32_e32 v83, v83, v94
	v_lshlrev_b32_e32 v84, 16, v84
	v_lshlrev_b32_e32 v95, 16, v95
	v_add_f32_e32 v84, v84, v95
	v_lshlrev_b32_e32 v85, 16, v85
	v_lshlrev_b32_e32 v96, 16, v96
	v_add_f32_e32 v85, v85, v96
	v_lshlrev_b32_e32 v86, 16, v86
	v_lshlrev_b32_e32 v97, 16, v97
	v_add_f32_e32 v86, v86, v97
	v_lshlrev_b32_e32 v87, 16, v87
	v_lshlrev_b32_e32 v98, 16, v98
	v_add_f32_e32 v87, v87, v98
	v_lshlrev_b32_e32 v88, 16, v88
	v_lshlrev_b32_e32 v99, 16, v99
	v_add_f32_e32 v88, v88, v99
	v_lshlrev_b32_e32 v89, 16, v89
	v_lshlrev_b32_e32 v100, 16, v100
	v_add_f32_e32 v89, v89, v100
	v_lshlrev_b32_e32 v90, 16, v90
	v_lshlrev_b32_e32 v101, 16, v101
	v_add_f32_e32 v90, v101, v90
	v_mul_f32_e32 v146, v81, v81
	v_fmac_f32_e32 v146, v80, v80
	v_mul_f32_e32 v147, v82, v82
	v_add_f32_e32 v146, v146, v147
	v_mul_f32_e32 v147, v83, v83
	v_add_f32_e32 v146, v146, v147
	v_mul_f32_e32 v147, v84, v84
	v_add_f32_e32 v146, v146, v147
	v_mul_f32_e32 v147, v85, v85
	v_add_f32_e32 v146, v146, v147
	s_nop 1
	v_add_f32_dpp v146, v146, v146 quad_perm:[1,0,3,2] row_mask:0xf bank_mask:0xf
	s_nop 1
	v_add_f32_dpp v146, v146, v146 quad_perm:[2,3,0,1] row_mask:0xf bank_mask:0xf
	s_nop 1
	v_add_f32_dpp v146, v146, v146 row_half_mirror row_mask:0xf bank_mask:0xf
	s_nop 1
	v_add_f32_dpp v146, v146, v146 row_mirror row_mask:0xf bank_mask:0xf
	v_mov_b32_e32 v147, v146
	s_nop 1
	v_permlane16_swap_b32 v146, v147
	v_add_f32_e32 v146, v146, v147
	v_mov_b32_e32 v147, v146
	s_nop 1
	v_permlane32_swap_b32 v146, v147
	v_add_f32_e32 v146, v146, v147
	v_fmamk_f32 v146, v146, 0x3b2aaaab, v218
	v_cmp_gt_f32_e32 vcc, s71, v146
	v_mul_f32_e32 v147, 0x4b800000, v146
	s_nop 0
	v_cndmask_b32_e32 v146, v146, v147, vcc
	v_rsq_f32_e32 v146, v146
	s_nop 0
	v_mul_f32_e32 v147, 0x45800000, v146
	v_cndmask_b32_e32 v146, v146, v147, vcc
	v_mad_i64_i32 v[148:149], s[8:9], v134, s70, v[8:9]
	v_mul_f32_e32 v147, v80, v146
	v_mul_f32_e32 v147, v124, v147
	v_bfe_u32 v150, v147, 16, 1
	v_add3_u32 v147, v147, v150, s73
	global_store_short_d16_hi v[148:149], v147, off
	v_mul_f32_e32 v147, v81, v146
	v_mul_f32_e32 v147, v125, v147
	v_bfe_u32 v150, v147, 16, 1
	v_add3_u32 v147, v147, v150, s73
	global_store_short_d16_hi v[148:149], v147, off offset:128
	v_mul_f32_e32 v147, v82, v146
	v_mul_f32_e32 v147, v126, v147
	v_bfe_u32 v150, v147, 16, 1
	v_add3_u32 v147, v147, v150, s73
	global_store_short_d16_hi v[148:149], v147, off offset:256
	v_mul_f32_e32 v147, v83, v146
	v_mul_f32_e32 v147, v127, v147
	v_bfe_u32 v150, v147, 16, 1
	v_add3_u32 v147, v147, v150, s73
	global_store_short_d16_hi v[148:149], v147, off offset:384
	v_mul_f32_e32 v147, v84, v146
	v_mul_f32_e32 v147, v128, v147
	v_bfe_u32 v150, v147, 16, 1
	v_add3_u32 v147, v147, v150, s73
	global_store_short_d16_hi v[148:149], v147, off offset:512
	v_mul_f32_e32 v147, v85, v146
	v_mul_f32_e32 v147, v129, v147
	v_bfe_u32 v150, v147, 16, 1
	v_add3_u32 v147, v147, v150, s73
	global_store_short_d16_hi v[148:149], v147, off offset:640
	v_mul_f32_e32 v146, v86, v86
	v_mul_f32_e32 v147, v87, v87
	v_add_f32_e32 v146, v146, v147
	v_mul_f32_e32 v147, v88, v88
	v_add_f32_e32 v146, v146, v147
	v_mul_f32_e32 v147, v89, v89
	v_add_f32_e32 v146, v146, v147
	s_nop 1
	v_add_f32_dpp v146, v146, v146 quad_perm:[1,0,3,2] row_mask:0xf bank_mask:0xf
	s_nop 1
	v_add_f32_dpp v146, v146, v146 quad_perm:[2,3,0,1] row_mask:0xf bank_mask:0xf
	s_nop 1
	v_add_f32_dpp v146, v146, v146 row_half_mirror row_mask:0xf bank_mask:0xf
	s_nop 1
	v_add_f32_dpp v146, v146, v146 row_mirror row_mask:0xf bank_mask:0xf
	v_mov_b32_e32 v147, v146
	s_nop 1
	v_permlane16_swap_b32 v146, v147
	v_add_f32_e32 v146, v146, v147
	v_mov_b32_e32 v147, v146
	s_nop 1
	v_permlane32_swap_b32 v146, v147
	v_add_f32_e32 v146, v146, v147
	v_fmamk_f32 v146, v146, 0x3b800000, v218
	v_cmp_gt_f32_e32 vcc, s71, v146
	v_mul_f32_e32 v147, 0x4b800000, v146
	s_nop 0
	v_cndmask_b32_e32 v146, v146, v147, vcc
	v_rsq_f32_e32 v146, v146
	s_nop 0
	v_mul_f32_e32 v147, 0x45800000, v146
	v_cndmask_b32_e32 v146, v146, v147, vcc
	v_ashrrev_i32_e32 v151, 31, v134
	v_mov_b32_e32 v150, v134
	v_lshlrev_b64 v[148:149], 9, v[150:151]
	v_lshl_add_u64 v[148:149], v[10:11], 0, v[148:149]
	v_lshlrev_b64 v[152:153], 10, v[150:151]
	s_waitcnt lgkmcnt(0)
	v_lshl_add_u64 v[152:153], s[10:11], 0, v[152:153]
	v_lshlrev_b32_e32 v154, 2, v6
	v_mov_b32_e32 v155, v3
	v_lshl_add_u64 v[154:155], v[152:153], 0, v[154:155]
	s_mov_b64 s[8:9], 0x7000000
	v_lshl_add_u64 v[154:155], v[154:155], 0, s[8:9]
	v_mul_f32_e32 v147, v86, v146
	v_mul_f32_e32 v147, v130, v147
	v_bfe_u32 v150, v147, 16, 1
	v_add3_u32 v150, v147, v150, s73
	global_store_short_d16_hi v[148:149], v150, off
	global_store_dword v[154:155], v147, off
	v_mul_f32_e32 v147, v87, v146
	v_mul_f32_e32 v147, v131, v147
	v_bfe_u32 v150, v147, 16, 1
	v_add3_u32 v150, v147, v150, s73
	global_store_short_d16_hi v[148:149], v150, off offset:128
	global_store_dword v[154:155], v147, off offset:256
	v_mul_f32_e32 v147, v88, v146
	v_mul_f32_e32 v147, v132, v147
	v_bfe_u32 v150, v147, 16, 1
	v_add3_u32 v150, v147, v150, s73
	global_store_short_d16_hi v[148:149], v150, off offset:256
	global_store_dword v[154:155], v147, off offset:512
	v_mul_f32_e32 v147, v89, v146
	v_mul_f32_e32 v147, v133, v147
	v_bfe_u32 v150, v147, 16, 1
	v_add3_u32 v150, v147, v150, s73
	global_store_short_d16_hi v[148:149], v150, off offset:384
	global_store_dword v[154:155], v147, off offset:768
	s_and_saveexec_b64 s[8:9], s[4:5]
	v_bfe_u32 v147, v90, 16, 1
	v_add3_u32 v147, v90, v147, s73
	global_store_short_d16_hi v[136:137], v147, off offset:1280
	s_movk_i32 s3, 0xfc80
	v_mad_i64_i32 v[148:149], s[12:13], v134, s3, v[152:153]
	v_lshlrev_b32_e32 v150, 2, v6
	v_mov_b32_e32 v151, v3
	v_lshl_add_u64 v[148:149], v[148:149], 0, v[150:151]
	v_add_co_u32_e32 v148, vcc, 0x7400000, v148
	s_nop 1
	v_addc_co_u32_e32 v149, vcc, 0, v149, vcc
	global_store_dword v[148:149], v90, off
	s_or_b64 exec, exec, s[8:9]
	v_lshlrev_b32_e32 v102, 16, v102
	v_lshlrev_b32_e32 v113, 16, v113
	v_add_f32_e32 v102, v102, v113
	v_lshlrev_b32_e32 v103, 16, v103
	v_lshlrev_b32_e32 v114, 16, v114
	v_add_f32_e32 v103, v103, v114
	v_lshlrev_b32_e32 v104, 16, v104
	v_lshlrev_b32_e32 v115, 16, v115
	v_add_f32_e32 v104, v104, v115
	v_lshlrev_b32_e32 v105, 16, v105
	v_lshlrev_b32_e32 v116, 16, v116
	v_add_f32_e32 v105, v105, v116
	v_lshlrev_b32_e32 v106, 16, v106
	v_lshlrev_b32_e32 v117, 16, v117
	v_add_f32_e32 v106, v106, v117
	v_lshlrev_b32_e32 v107, 16, v107
	v_lshlrev_b32_e32 v118, 16, v118
	v_add_f32_e32 v107, v107, v118
	v_lshlrev_b32_e32 v108, 16, v108
	v_lshlrev_b32_e32 v119, 16, v119
	v_add_f32_e32 v108, v108, v119
	v_lshlrev_b32_e32 v109, 16, v109
	v_lshlrev_b32_e32 v120, 16, v120
	v_add_f32_e32 v109, v109, v120
	v_lshlrev_b32_e32 v110, 16, v110
	v_lshlrev_b32_e32 v121, 16, v121
	v_add_f32_e32 v110, v110, v121
	v_lshlrev_b32_e32 v111, 16, v111
	v_lshlrev_b32_e32 v122, 16, v122
	v_add_f32_e32 v111, v111, v122
	v_lshlrev_b32_e32 v112, 16, v112
	v_lshlrev_b32_e32 v123, 16, v123
	v_add_f32_e32 v112, v123, v112
	v_mul_f32_e32 v146, v103, v103
	v_fmac_f32_e32 v146, v102, v102
	v_mul_f32_e32 v147, v104, v104
	v_add_f32_e32 v146, v146, v147
	v_mul_f32_e32 v147, v105, v105
	v_add_f32_e32 v146, v146, v147
	v_mul_f32_e32 v147, v106, v106
	v_add_f32_e32 v146, v146, v147
	v_mul_f32_e32 v147, v107, v107
	v_add_f32_e32 v146, v146, v147
	s_nop 1
	v_add_f32_dpp v146, v146, v146 quad_perm:[1,0,3,2] row_mask:0xf bank_mask:0xf
	s_nop 1
	v_add_f32_dpp v146, v146, v146 quad_perm:[2,3,0,1] row_mask:0xf bank_mask:0xf
	s_nop 1
	v_add_f32_dpp v146, v146, v146 row_half_mirror row_mask:0xf bank_mask:0xf
	s_nop 1
	v_add_f32_dpp v146, v146, v146 row_mirror row_mask:0xf bank_mask:0xf
	v_mov_b32_e32 v147, v146
	s_nop 1
	v_permlane16_swap_b32 v146, v147
	v_add_f32_e32 v146, v146, v147
	v_mov_b32_e32 v147, v146
	s_nop 1
	v_permlane32_swap_b32 v146, v147
	v_add_f32_e32 v146, v146, v147
	v_fmamk_f32 v146, v146, 0x3b2aaaab, v218
	v_cmp_gt_f32_e32 vcc, s71, v146
	v_mul_f32_e32 v147, 0x4b800000, v146
	s_nop 0
	v_cndmask_b32_e32 v146, v146, v147, vcc
	v_rsq_f32_e32 v146, v146
	s_nop 0
	v_mul_f32_e32 v147, 0x45800000, v146
	v_cndmask_b32_e32 v146, v146, v147, vcc
	v_mad_i64_i32 v[148:149], s[8:9], v135, s70, v[8:9]
	v_mul_f32_e32 v147, v102, v146
	v_mul_f32_e32 v147, v124, v147
	v_bfe_u32 v150, v147, 16, 1
	v_add3_u32 v147, v147, v150, s73
	global_store_short_d16_hi v[148:149], v147, off
	v_mul_f32_e32 v147, v103, v146
	v_mul_f32_e32 v147, v125, v147
	v_bfe_u32 v150, v147, 16, 1
	v_add3_u32 v147, v147, v150, s73
	global_store_short_d16_hi v[148:149], v147, off offset:128
	v_mul_f32_e32 v147, v104, v146
	v_mul_f32_e32 v147, v126, v147
	v_bfe_u32 v150, v147, 16, 1
	v_add3_u32 v147, v147, v150, s73
	global_store_short_d16_hi v[148:149], v147, off offset:256
	v_mul_f32_e32 v147, v105, v146
	v_mul_f32_e32 v147, v127, v147
	v_bfe_u32 v150, v147, 16, 1
	v_add3_u32 v147, v147, v150, s73
	global_store_short_d16_hi v[148:149], v147, off offset:384
	v_mul_f32_e32 v147, v106, v146
	v_mul_f32_e32 v147, v128, v147
	v_bfe_u32 v150, v147, 16, 1
	v_add3_u32 v147, v147, v150, s73
	global_store_short_d16_hi v[148:149], v147, off offset:512
	v_mul_f32_e32 v147, v107, v146
	v_mul_f32_e32 v147, v129, v147
	v_bfe_u32 v150, v147, 16, 1
	v_add3_u32 v147, v147, v150, s73
	global_store_short_d16_hi v[148:149], v147, off offset:640
	v_mul_f32_e32 v146, v108, v108
	v_mul_f32_e32 v147, v109, v109
	v_add_f32_e32 v146, v146, v147
	v_mul_f32_e32 v147, v110, v110
	v_add_f32_e32 v146, v146, v147
	v_mul_f32_e32 v147, v111, v111
	v_add_f32_e32 v146, v146, v147
	s_nop 1
	v_add_f32_dpp v146, v146, v146 quad_perm:[1,0,3,2] row_mask:0xf bank_mask:0xf
	s_nop 1
	v_add_f32_dpp v146, v146, v146 quad_perm:[2,3,0,1] row_mask:0xf bank_mask:0xf
	s_nop 1
	v_add_f32_dpp v146, v146, v146 row_half_mirror row_mask:0xf bank_mask:0xf
	s_nop 1
	v_add_f32_dpp v146, v146, v146 row_mirror row_mask:0xf bank_mask:0xf
	v_mov_b32_e32 v147, v146
	s_nop 1
	v_permlane16_swap_b32 v146, v147
	v_add_f32_e32 v146, v146, v147
	v_mov_b32_e32 v147, v146
	s_nop 1
	v_permlane32_swap_b32 v146, v147
	v_add_f32_e32 v146, v146, v147
	v_fmamk_f32 v146, v146, 0x3b800000, v218
	v_cmp_gt_f32_e32 vcc, s71, v146
	v_mul_f32_e32 v147, 0x4b800000, v146
	s_nop 0
	v_cndmask_b32_e32 v146, v146, v147, vcc
	v_rsq_f32_e32 v146, v146
	s_nop 0
	v_mul_f32_e32 v147, 0x45800000, v146
	v_cndmask_b32_e32 v146, v146, v147, vcc
	v_ashrrev_i32_e32 v151, 31, v135
	v_mov_b32_e32 v150, v135
	v_lshlrev_b64 v[148:149], 9, v[150:151]
	v_lshl_add_u64 v[148:149], v[10:11], 0, v[148:149]
	v_lshlrev_b64 v[152:153], 10, v[150:151]
	s_waitcnt lgkmcnt(0)
	v_lshl_add_u64 v[152:153], s[10:11], 0, v[152:153]
	v_lshlrev_b32_e32 v154, 2, v6
	v_mov_b32_e32 v155, v3
	v_lshl_add_u64 v[154:155], v[152:153], 0, v[154:155]
	s_mov_b64 s[8:9], 0x7000000
	v_lshl_add_u64 v[154:155], v[154:155], 0, s[8:9]
	v_mul_f32_e32 v147, v108, v146
	v_mul_f32_e32 v147, v130, v147
	v_bfe_u32 v150, v147, 16, 1
	v_add3_u32 v150, v147, v150, s73
	global_store_short_d16_hi v[148:149], v150, off
	global_store_dword v[154:155], v147, off
	v_mul_f32_e32 v147, v109, v146
	v_mul_f32_e32 v147, v131, v147
	v_bfe_u32 v150, v147, 16, 1
	v_add3_u32 v150, v147, v150, s73
	global_store_short_d16_hi v[148:149], v150, off offset:128
	global_store_dword v[154:155], v147, off offset:256
	v_mul_f32_e32 v147, v110, v146
	v_mul_f32_e32 v147, v132, v147
	v_bfe_u32 v150, v147, 16, 1
	v_add3_u32 v150, v147, v150, s73
	global_store_short_d16_hi v[148:149], v150, off offset:256
	global_store_dword v[154:155], v147, off offset:512
	v_mul_f32_e32 v147, v111, v146
	v_mul_f32_e32 v147, v133, v147
	v_bfe_u32 v150, v147, 16, 1
	v_add3_u32 v150, v147, v150, s73
	global_store_short_d16_hi v[148:149], v150, off offset:384
	global_store_dword v[154:155], v147, off offset:768
	s_and_saveexec_b64 s[8:9], s[4:5]
	v_bfe_u32 v147, v112, 16, 1
	v_add3_u32 v147, v112, v147, s73
	global_store_short_d16_hi v[138:139], v147, off offset:1280
	s_movk_i32 s3, 0xfc80
	v_mad_i64_i32 v[148:149], s[12:13], v135, s3, v[152:153]
	v_lshlrev_b32_e32 v150, 2, v6
	v_mov_b32_e32 v151, v3
	v_lshl_add_u64 v[148:149], v[148:149], 0, v[150:151]
	v_add_co_u32_e32 v148, vcc, 0x7400000, v148
	s_nop 1
	v_addc_co_u32_e32 v149, vcc, 0, v149, vcc
	global_store_dword v[148:149], v112, off
	s_or_b64 exec, exec, s[8:9]
	s_waitcnt vmcnt(0)
	v_lshlrev_b32_e32 v188, 16, v188
	v_lshlrev_b32_e32 v199, 16, v199
	v_add_f32_e32 v188, v188, v199
	v_lshlrev_b32_e32 v189, 16, v189
	v_lshlrev_b32_e32 v200, 16, v200
	v_add_f32_e32 v189, v189, v200
	v_lshlrev_b32_e32 v190, 16, v190
	v_lshlrev_b32_e32 v201, 16, v201
	v_add_f32_e32 v190, v190, v201
	v_lshlrev_b32_e32 v191, 16, v191
	v_lshlrev_b32_e32 v202, 16, v202
	v_add_f32_e32 v191, v191, v202
	v_lshlrev_b32_e32 v192, 16, v192
	v_lshlrev_b32_e32 v203, 16, v203
	v_add_f32_e32 v192, v192, v203
	v_lshlrev_b32_e32 v193, 16, v193
	v_lshlrev_b32_e32 v204, 16, v204
	v_add_f32_e32 v193, v193, v204
	v_lshlrev_b32_e32 v194, 16, v194
	v_lshlrev_b32_e32 v205, 16, v205
	v_add_f32_e32 v194, v194, v205
	v_lshlrev_b32_e32 v195, 16, v195
	v_lshlrev_b32_e32 v206, 16, v206
	v_add_f32_e32 v195, v195, v206
	v_lshlrev_b32_e32 v196, 16, v196
	v_lshlrev_b32_e32 v207, 16, v207
	v_add_f32_e32 v196, v196, v207
	v_lshlrev_b32_e32 v197, 16, v197
	v_lshlrev_b32_e32 v208, 16, v208
	v_add_f32_e32 v197, v197, v208
	v_lshlrev_b32_e32 v198, 16, v198
	v_lshlrev_b32_e32 v209, 16, v209
	v_add_f32_e32 v198, v209, v198
	v_mul_f32_e32 v146, v189, v189
	v_fmac_f32_e32 v146, v188, v188
	v_mul_f32_e32 v147, v190, v190
	v_add_f32_e32 v146, v146, v147
	v_mul_f32_e32 v147, v191, v191
	v_add_f32_e32 v146, v146, v147
	v_mul_f32_e32 v147, v192, v192
	v_add_f32_e32 v146, v146, v147
	v_mul_f32_e32 v147, v193, v193
	v_add_f32_e32 v146, v146, v147
	s_nop 1
	v_add_f32_dpp v146, v146, v146 quad_perm:[1,0,3,2] row_mask:0xf bank_mask:0xf
	s_nop 1
	v_add_f32_dpp v146, v146, v146 quad_perm:[2,3,0,1] row_mask:0xf bank_mask:0xf
	s_nop 1
	v_add_f32_dpp v146, v146, v146 row_half_mirror row_mask:0xf bank_mask:0xf
	s_nop 1
	v_add_f32_dpp v146, v146, v146 row_mirror row_mask:0xf bank_mask:0xf
	v_mov_b32_e32 v147, v146
	s_nop 1
	v_permlane16_swap_b32 v146, v147
	v_add_f32_e32 v146, v146, v147
	v_mov_b32_e32 v147, v146
	s_nop 1
	v_permlane32_swap_b32 v146, v147
	v_add_f32_e32 v146, v146, v147
	v_fmamk_f32 v146, v146, 0x3b2aaaab, v218
	v_cmp_gt_f32_e32 vcc, s71, v146
	v_mul_f32_e32 v147, 0x4b800000, v146
	s_nop 0
	v_cndmask_b32_e32 v146, v146, v147, vcc
	v_rsq_f32_e32 v146, v146
	s_nop 0
	v_mul_f32_e32 v147, 0x45800000, v146
	v_cndmask_b32_e32 v146, v146, v147, vcc
	v_mad_i64_i32 v[148:149], s[8:9], v248, s70, v[8:9]
	v_mul_f32_e32 v147, v188, v146
	v_mul_f32_e32 v147, v124, v147
	v_bfe_u32 v150, v147, 16, 1
	v_add3_u32 v147, v147, v150, s73
	global_store_short_d16_hi v[148:149], v147, off
	v_mul_f32_e32 v147, v189, v146
	v_mul_f32_e32 v147, v125, v147
	v_bfe_u32 v150, v147, 16, 1
	v_add3_u32 v147, v147, v150, s73
	global_store_short_d16_hi v[148:149], v147, off offset:128
	v_mul_f32_e32 v147, v190, v146
	v_mul_f32_e32 v147, v126, v147
	v_bfe_u32 v150, v147, 16, 1
	v_add3_u32 v147, v147, v150, s73
	global_store_short_d16_hi v[148:149], v147, off offset:256
	v_mul_f32_e32 v147, v191, v146
	v_mul_f32_e32 v147, v127, v147
	v_bfe_u32 v150, v147, 16, 1
	v_add3_u32 v147, v147, v150, s73
	global_store_short_d16_hi v[148:149], v147, off offset:384
	v_mul_f32_e32 v147, v192, v146
	v_mul_f32_e32 v147, v128, v147
	v_bfe_u32 v150, v147, 16, 1
	v_add3_u32 v147, v147, v150, s73
	global_store_short_d16_hi v[148:149], v147, off offset:512
	v_mul_f32_e32 v147, v193, v146
	v_mul_f32_e32 v147, v129, v147
	v_bfe_u32 v150, v147, 16, 1
	v_add3_u32 v147, v147, v150, s73
	global_store_short_d16_hi v[148:149], v147, off offset:640
	v_mul_f32_e32 v146, v194, v194
	v_mul_f32_e32 v147, v195, v195
	v_add_f32_e32 v146, v146, v147
	v_mul_f32_e32 v147, v196, v196
	v_add_f32_e32 v146, v146, v147
	v_mul_f32_e32 v147, v197, v197
	v_add_f32_e32 v146, v146, v147
	s_nop 1
	v_add_f32_dpp v146, v146, v146 quad_perm:[1,0,3,2] row_mask:0xf bank_mask:0xf
	s_nop 1
	v_add_f32_dpp v146, v146, v146 quad_perm:[2,3,0,1] row_mask:0xf bank_mask:0xf
	s_nop 1
	v_add_f32_dpp v146, v146, v146 row_half_mirror row_mask:0xf bank_mask:0xf
	s_nop 1
	v_add_f32_dpp v146, v146, v146 row_mirror row_mask:0xf bank_mask:0xf
	v_mov_b32_e32 v147, v146
	s_nop 1
	v_permlane16_swap_b32 v146, v147
	v_add_f32_e32 v146, v146, v147
	v_mov_b32_e32 v147, v146
	s_nop 1
	v_permlane32_swap_b32 v146, v147
	v_add_f32_e32 v146, v146, v147
	v_fmamk_f32 v146, v146, 0x3b800000, v218
	v_cmp_gt_f32_e32 vcc, s71, v146
	v_mul_f32_e32 v147, 0x4b800000, v146
	s_nop 0
	v_cndmask_b32_e32 v146, v146, v147, vcc
	v_rsq_f32_e32 v146, v146
	s_nop 0
	v_mul_f32_e32 v147, 0x45800000, v146
	v_cndmask_b32_e32 v146, v146, v147, vcc
	v_ashrrev_i32_e32 v151, 31, v248
	v_mov_b32_e32 v150, v248
	v_lshlrev_b64 v[148:149], 9, v[150:151]
	v_lshl_add_u64 v[148:149], v[10:11], 0, v[148:149]
	v_mul_f32_e32 v147, v194, v146
	v_mul_f32_e32 v147, v130, v147
	v_bfe_u32 v150, v147, 16, 1
	v_add3_u32 v150, v147, v150, s73
	global_store_short_d16_hi v[148:149], v150, off
	v_mul_f32_e32 v147, v195, v146
	v_mul_f32_e32 v147, v131, v147
	v_bfe_u32 v150, v147, 16, 1
	v_add3_u32 v150, v147, v150, s73
	global_store_short_d16_hi v[148:149], v150, off offset:128
	v_mul_f32_e32 v147, v196, v146
	v_mul_f32_e32 v147, v132, v147
	v_bfe_u32 v150, v147, 16, 1
	v_add3_u32 v150, v147, v150, s73
	global_store_short_d16_hi v[148:149], v150, off offset:256
	v_mul_f32_e32 v147, v197, v146
	v_mul_f32_e32 v147, v133, v147
	v_bfe_u32 v150, v147, 16, 1
	v_add3_u32 v150, v147, v150, s73
	global_store_short_d16_hi v[148:149], v150, off offset:384
	s_and_saveexec_b64 s[8:9], s[4:5]
	v_bfe_u32 v147, v198, 16, 1
	v_add3_u32 v147, v198, v147, s73
	global_store_short_d16_hi v[250:251], v147, off offset:1280
	s_or_b64 exec, exec, s[8:9]
	v_lshlrev_b32_e32 v210, 16, v210
	v_lshlrev_b32_e32 v237, 16, v237
	v_add_f32_e32 v210, v210, v237
	v_lshlrev_b32_e32 v211, 16, v211
	v_lshlrev_b32_e32 v238, 16, v238
	v_add_f32_e32 v211, v211, v238
	v_lshlrev_b32_e32 v212, 16, v212
	v_lshlrev_b32_e32 v239, 16, v239
	v_add_f32_e32 v212, v212, v239
	v_lshlrev_b32_e32 v213, 16, v213
	v_lshlrev_b32_e32 v240, 16, v240
	v_add_f32_e32 v213, v213, v240
	v_lshlrev_b32_e32 v214, 16, v214
	v_lshlrev_b32_e32 v241, 16, v241
	v_add_f32_e32 v214, v214, v241
	v_lshlrev_b32_e32 v215, 16, v215
	v_lshlrev_b32_e32 v242, 16, v242
	v_add_f32_e32 v215, v215, v242
	v_lshlrev_b32_e32 v216, 16, v216
	v_lshlrev_b32_e32 v243, 16, v243
	v_add_f32_e32 v216, v216, v243
	v_lshlrev_b32_e32 v217, 16, v217
	v_lshlrev_b32_e32 v244, 16, v244
	v_add_f32_e32 v217, v217, v244
	v_lshlrev_b32_e32 v234, 16, v234
	v_lshlrev_b32_e32 v245, 16, v245
	v_add_f32_e32 v234, v234, v245
	v_lshlrev_b32_e32 v235, 16, v235
	v_lshlrev_b32_e32 v246, 16, v246
	v_add_f32_e32 v235, v235, v246
	v_lshlrev_b32_e32 v236, 16, v236
	v_lshlrev_b32_e32 v247, 16, v247
	v_add_f32_e32 v236, v247, v236
	v_mul_f32_e32 v146, v211, v211
	v_fmac_f32_e32 v146, v210, v210
	v_mul_f32_e32 v147, v212, v212
	v_add_f32_e32 v146, v146, v147
	v_mul_f32_e32 v147, v213, v213
	v_add_f32_e32 v146, v146, v147
	v_mul_f32_e32 v147, v214, v214
	v_add_f32_e32 v146, v146, v147
	v_mul_f32_e32 v147, v215, v215
	v_add_f32_e32 v146, v146, v147
	s_nop 1
	v_add_f32_dpp v146, v146, v146 quad_perm:[1,0,3,2] row_mask:0xf bank_mask:0xf
	s_nop 1
	v_add_f32_dpp v146, v146, v146 quad_perm:[2,3,0,1] row_mask:0xf bank_mask:0xf
	s_nop 1
	v_add_f32_dpp v146, v146, v146 row_half_mirror row_mask:0xf bank_mask:0xf
	s_nop 1
	v_add_f32_dpp v146, v146, v146 row_mirror row_mask:0xf bank_mask:0xf
	v_mov_b32_e32 v147, v146
	s_nop 1
	v_permlane16_swap_b32 v146, v147
	v_add_f32_e32 v146, v146, v147
	v_mov_b32_e32 v147, v146
	s_nop 1
	v_permlane32_swap_b32 v146, v147
	v_add_f32_e32 v146, v146, v147
	v_fmamk_f32 v146, v146, 0x3b2aaaab, v218
	v_cmp_gt_f32_e32 vcc, s71, v146
	v_mul_f32_e32 v147, 0x4b800000, v146
	s_nop 0
	v_cndmask_b32_e32 v146, v146, v147, vcc
	v_rsq_f32_e32 v146, v146
	s_nop 0
	v_mul_f32_e32 v147, 0x45800000, v146
	v_cndmask_b32_e32 v146, v146, v147, vcc
	v_mad_i64_i32 v[148:149], s[8:9], v249, s70, v[8:9]
	v_mul_f32_e32 v147, v210, v146
	v_mul_f32_e32 v147, v124, v147
	v_bfe_u32 v150, v147, 16, 1
	v_add3_u32 v147, v147, v150, s73
	global_store_short_d16_hi v[148:149], v147, off
	v_mul_f32_e32 v147, v211, v146
	v_mul_f32_e32 v147, v125, v147
	v_bfe_u32 v150, v147, 16, 1
	v_add3_u32 v147, v147, v150, s73
	global_store_short_d16_hi v[148:149], v147, off offset:128
	v_mul_f32_e32 v147, v212, v146
	v_mul_f32_e32 v147, v126, v147
	v_bfe_u32 v150, v147, 16, 1
	v_add3_u32 v147, v147, v150, s73
	global_store_short_d16_hi v[148:149], v147, off offset:256
	v_mul_f32_e32 v147, v213, v146
	v_mul_f32_e32 v147, v127, v147
	v_bfe_u32 v150, v147, 16, 1
	v_add3_u32 v147, v147, v150, s73
	global_store_short_d16_hi v[148:149], v147, off offset:384
	v_mul_f32_e32 v147, v214, v146
	v_mul_f32_e32 v147, v128, v147
	v_bfe_u32 v150, v147, 16, 1
	v_add3_u32 v147, v147, v150, s73
	global_store_short_d16_hi v[148:149], v147, off offset:512
	v_mul_f32_e32 v147, v215, v146
	v_mul_f32_e32 v147, v129, v147
	v_bfe_u32 v150, v147, 16, 1
	v_add3_u32 v147, v147, v150, s73
	global_store_short_d16_hi v[148:149], v147, off offset:640
	v_mul_f32_e32 v146, v216, v216
	v_mul_f32_e32 v147, v217, v217
	v_add_f32_e32 v146, v146, v147
	v_mul_f32_e32 v147, v234, v234
	v_add_f32_e32 v146, v146, v147
	v_mul_f32_e32 v147, v235, v235
	v_add_f32_e32 v146, v146, v147
	s_nop 1
	v_add_f32_dpp v146, v146, v146 quad_perm:[1,0,3,2] row_mask:0xf bank_mask:0xf
	s_nop 1
	v_add_f32_dpp v146, v146, v146 quad_perm:[2,3,0,1] row_mask:0xf bank_mask:0xf
	s_nop 1
	v_add_f32_dpp v146, v146, v146 row_half_mirror row_mask:0xf bank_mask:0xf
	s_nop 1
	v_add_f32_dpp v146, v146, v146 row_mirror row_mask:0xf bank_mask:0xf
	v_mov_b32_e32 v147, v146
	s_nop 1
	v_permlane16_swap_b32 v146, v147
	v_add_f32_e32 v146, v146, v147
	v_mov_b32_e32 v147, v146
	s_nop 1
	v_permlane32_swap_b32 v146, v147
	v_add_f32_e32 v146, v146, v147
	v_fmamk_f32 v146, v146, 0x3b800000, v218
	v_cmp_gt_f32_e32 vcc, s71, v146
	v_mul_f32_e32 v147, 0x4b800000, v146
	s_nop 0
	v_cndmask_b32_e32 v146, v146, v147, vcc
	v_rsq_f32_e32 v146, v146
	s_nop 0
	v_mul_f32_e32 v147, 0x45800000, v146
	v_cndmask_b32_e32 v146, v146, v147, vcc
	v_ashrrev_i32_e32 v151, 31, v249
	v_mov_b32_e32 v150, v249
	v_lshlrev_b64 v[148:149], 9, v[150:151]
	v_lshl_add_u64 v[148:149], v[10:11], 0, v[148:149]
	v_mul_f32_e32 v147, v216, v146
	v_mul_f32_e32 v147, v130, v147
	v_bfe_u32 v150, v147, 16, 1
	v_add3_u32 v150, v147, v150, s73
	global_store_short_d16_hi v[148:149], v150, off
	v_mul_f32_e32 v147, v217, v146
	v_mul_f32_e32 v147, v131, v147
	v_bfe_u32 v150, v147, 16, 1
	v_add3_u32 v150, v147, v150, s73
	global_store_short_d16_hi v[148:149], v150, off offset:128
	v_mul_f32_e32 v147, v234, v146
	v_mul_f32_e32 v147, v132, v147
	v_bfe_u32 v150, v147, 16, 1
	v_add3_u32 v150, v147, v150, s73
	global_store_short_d16_hi v[148:149], v150, off offset:256
	v_mul_f32_e32 v147, v235, v146
	v_mul_f32_e32 v147, v133, v147
	v_bfe_u32 v150, v147, 16, 1
	v_add3_u32 v150, v147, v150, s73
	global_store_short_d16_hi v[148:149], v150, off offset:384
	s_and_saveexec_b64 s[8:9], s[4:5]
	v_bfe_u32 v147, v236, 16, 1
	v_add3_u32 v147, v236, v147, s73
	global_store_short_d16_hi v[252:253], v147, off offset:1280
	s_or_b64 exec, exec, s[8:9]
	s_branch .LBB0_711

.LBB0_700:
	s_movk_i32 s3, 0x600
	v_mad_i64_i32 v[20:21], s[8:9], v4, s3, v[16:17]
	v_mad_i64_i32 v[22:23], s[8:9], v4, s3, v[18:19]
	global_load_ushort v2, v[20:21], off
	global_load_ushort v24, v[22:23], off
	v_ashrrev_i32_e32 v5, 31, v4
	s_movk_i32 s3, 0x1000
	global_load_ushort v25, v[22:23], off offset:128
	s_waitcnt vmcnt(0)
	v_lshlrev_b32_e32 v2, 16, v2
	v_lshlrev_b32_e32 v24, 16, v24
	v_add_f32_e32 v2, v2, v24
	global_load_ushort v24, v[20:21], off offset:128
	v_lshlrev_b32_e32 v25, 16, v25
	s_waitcnt vmcnt(0)
	v_lshlrev_b32_e32 v24, 16, v24
	v_add_f32_e32 v30, v24, v25
	global_load_ushort v24, v[20:21], off offset:256
	global_load_ushort v25, v[20:21], off offset:384
	global_load_ushort v26, v[22:23], off offset:256
	global_load_ushort v27, v[22:23], off offset:384
	v_mul_f32_e32 v28, v30, v30
	v_fmac_f32_e32 v28, v2, v2
	s_waitcnt vmcnt(3)
	v_lshlrev_b32_e32 v24, 16, v24
	s_waitcnt vmcnt(2)
	v_lshlrev_b32_e32 v25, 16, v25
	s_waitcnt vmcnt(0)
	v_lshlrev_b32_e32 v27, 16, v27
	v_lshlrev_b32_e32 v26, 16, v26
	v_pk_add_f32 v[26:27], v[24:25], v[26:27]
	s_nop 0
	v_pk_mul_f32 v[24:25], v[26:27], v[26:27]
	s_nop 0
	v_add_f32_e32 v24, v28, v24
	v_add_f32_e32 v31, v24, v25
	global_load_ushort v24, v[20:21], off offset:512
	global_load_ushort v25, v[20:21], off offset:640
	global_load_ushort v28, v[22:23], off offset:512
	global_load_ushort v29, v[22:23], off offset:640
	global_load_dword v32, v[12:13], off
	s_waitcnt vmcnt(4)
	v_lshlrev_b32_e32 v24, 16, v24
	s_waitcnt vmcnt(3)
	v_lshlrev_b32_e32 v25, 16, v25
	s_waitcnt vmcnt(1)
	v_lshlrev_b32_e32 v29, 16, v29
	v_lshlrev_b32_e32 v28, 16, v28
	v_pk_add_f32 v[28:29], v[24:25], v[28:29]
	s_nop 0
	v_pk_mul_f32 v[24:25], v[28:29], v[28:29]
	s_nop 0
	v_add_f32_e32 v24, v31, v24
	v_add_f32_e32 v24, v24, v25
	s_nop 1
	v_add_f32_dpp v24, v24, v24 quad_perm:[1,0,3,2] row_mask:0xf bank_mask:0xf
	s_nop 1
	v_add_f32_dpp v24, v24, v24 quad_perm:[2,3,0,1] row_mask:0xf bank_mask:0xf
	s_nop 1
	v_add_f32_dpp v24, v24, v24 row_half_mirror row_mask:0xf bank_mask:0xf
	s_nop 1
	v_add_f32_dpp v24, v24, v24 row_mirror row_mask:0xf bank_mask:0xf
	v_mov_b32_e32 v25, v24
	s_nop 1
	v_permlane16_swap_b32 v24, v25
	v_add_f32_e32 v24, v24, v25
	v_mov_b32_e32 v25, v24
	s_nop 1
	v_permlane32_swap_b32 v24, v25
	v_add_f32_e32 v24, v24, v25
	v_fmamk_f32 v24, v24, 0x3b2aaaab, v218
	v_cmp_gt_f32_e32 vcc, s71, v24
	v_mul_f32_e32 v25, 0x4b800000, v24
	s_nop 0
	v_cndmask_b32_e32 v24, v24, v25, vcc
	v_rsq_f32_e32 v24, v24
	s_nop 0
	v_mul_f32_e32 v25, 0x45800000, v24
	v_cndmask_b32_e32 v31, v24, v25, vcc
	v_mul_f32_e32 v2, v2, v31
	s_waitcnt vmcnt(0)
	v_mul_f32_e32 v2, v32, v2
	v_bfe_u32 v32, v2, 16, 1
	v_mad_i64_i32 v[24:25], s[8:9], v4, s70, v[8:9]
	v_add3_u32 v2, v2, v32, s73
	global_store_short_d16_hi v[24:25], v2, off
	v_mul_f32_e32 v2, v30, v31
	global_load_dword v30, v[12:13], off offset:256
	s_waitcnt vmcnt(0)
	v_mul_f32_e32 v2, v30, v2
	v_bfe_u32 v30, v2, 16, 1
	v_add3_u32 v2, v2, v30, s73
	global_store_short_d16_hi v[24:25], v2, off offset:128
	v_mul_f32_e32 v2, v26, v31
	global_load_dword v26, v[12:13], off offset:512
	s_waitcnt vmcnt(0)
	v_mul_f32_e32 v2, v26, v2
	v_bfe_u32 v26, v2, 16, 1
	v_add3_u32 v2, v2, v26, s73
	global_load_dword v26, v[12:13], off offset:768
	s_nop 0
	global_store_short_d16_hi v[24:25], v2, off offset:256
	v_mul_f32_e32 v2, v27, v31
	s_waitcnt vmcnt(1)
	v_mul_f32_e32 v2, v26, v2
	v_bfe_u32 v26, v2, 16, 1
	v_add3_u32 v2, v2, v26, s73
	global_load_dword v26, v[12:13], off offset:1024
	s_nop 0
	global_store_short_d16_hi v[24:25], v2, off offset:384
	v_mul_f32_e32 v2, v28, v31
	s_waitcnt vmcnt(1)
	v_mul_f32_e32 v2, v26, v2
	v_bfe_u32 v26, v2, 16, 1
	v_add3_u32 v2, v2, v26, s73
	global_load_dword v26, v[12:13], off offset:1280
	s_nop 0
	global_store_short_d16_hi v[24:25], v2, off offset:512
	v_mul_f32_e32 v2, v29, v31
	s_waitcnt vmcnt(1)
	v_mul_f32_e32 v2, v26, v2
	v_bfe_u32 v26, v2, 16, 1
	v_add3_u32 v2, v2, v26, s73
	global_store_short_d16_hi v[24:25], v2, off offset:640
	global_load_ushort v2, v[20:21], off offset:896
	s_nop 0
	global_load_ushort v24, v[20:21], off offset:768
	s_waitcnt vmcnt(1)
	v_lshlrev_b32_e32 v25, 16, v2
	global_load_ushort v2, v[22:23], off offset:896
	global_load_ushort v26, v[22:23], off offset:768
	s_waitcnt vmcnt(2)
	v_lshlrev_b32_e32 v24, 16, v24
	s_waitcnt vmcnt(1)
	v_lshlrev_b32_e32 v27, 16, v2
	global_load_ushort v2, v[20:21], off offset:1152
	global_load_ushort v28, v[20:21], off offset:1024
	s_waitcnt vmcnt(2)
	v_lshlrev_b32_e32 v26, 16, v26
	v_pk_add_f32 v[24:25], v[24:25], v[26:27]
	s_waitcnt vmcnt(1)
	v_lshlrev_b32_e32 v29, 16, v2
	global_load_ushort v2, v[22:23], off offset:1152
	global_load_ushort v30, v[22:23], off offset:1024
	s_waitcnt vmcnt(2)
	v_lshlrev_b32_e32 v28, 16, v28
	v_pk_mul_f32 v[26:27], v[24:25], v[24:25]
	s_load_dwordx2 s[8:9], s[30:31], 0x170
	s_waitcnt vmcnt(1)
	v_lshlrev_b32_e32 v31, 16, v2
	s_waitcnt vmcnt(0)
	v_lshlrev_b32_e32 v30, 16, v30
	v_pk_add_f32 v[28:29], v[28:29], v[30:31]
	v_add_f32_e32 v2, v26, v27
	v_pk_mul_f32 v[30:31], v[28:29], v[28:29]
	s_nop 0
	v_add_f32_e32 v2, v2, v30
	v_add_f32_e32 v2, v2, v31
	s_nop 1
	v_add_f32_dpp v2, v2, v2 quad_perm:[1,0,3,2] row_mask:0xf bank_mask:0xf
	s_nop 1
	v_add_f32_dpp v2, v2, v2 quad_perm:[2,3,0,1] row_mask:0xf bank_mask:0xf
	s_nop 1
	v_add_f32_dpp v2, v2, v2 row_half_mirror row_mask:0xf bank_mask:0xf
	s_nop 1
	v_add_f32_dpp v2, v2, v2 row_mirror row_mask:0xf bank_mask:0xf
	v_mov_b32_e32 v26, v2
	s_nop 1
	v_permlane16_swap_b32 v2, v26
	v_add_f32_e32 v2, v2, v26
	v_mov_b32_e32 v26, v2
	s_nop 1
	v_permlane32_swap_b32 v2, v26
	v_add_f32_e32 v2, v2, v26
	v_fmamk_f32 v2, v2, 0x3b800000, v218
	v_cmp_gt_f32_e32 vcc, s71, v2
	v_mul_f32_e32 v26, 0x4b800000, v2
	s_nop 0
	v_cndmask_b32_e32 v2, v2, v26, vcc
	v_rsq_f32_e32 v2, v2
	s_nop 0
	v_mul_f32_e32 v26, 0x45800000, v2
	v_cndmask_b32_e32 v39, v2, v26, vcc
	v_lshlrev_b64 v[26:27], 9, v[4:5]
	v_lshl_add_u64 v[30:31], v[10:11], 0, v[26:27]
	v_lshlrev_b64 v[26:27], 10, v[4:5]
	v_mul_f32_e32 v5, v24, v39
	global_load_dword v24, v[14:15], off
	v_lshl_add_u64 v[26:27], s[8:9], 0, v[26:27]
	v_lshlrev_b32_e32 v2, 2, v6
	v_lshl_add_u64 v[32:33], v[26:27], 0, v[2:3]
	s_mov_b64 s[8:9], 0x7000000
	v_cmp_gt_i32_e32 vcc, s3, v4
	v_lshl_add_u64 v[32:33], v[32:33], 0, s[8:9]
	s_waitcnt vmcnt(0)
	v_mul_f32_e32 v5, v24, v5
	v_bfe_u32 v24, v5, 16, 1
	v_add3_u32 v24, v5, v24, s73
	global_store_short_d16_hi v[30:31], v24, off
	s_and_saveexec_b64 s[8:9], vcc
	s_cbranch_execz .LBB0_702
	global_store_dword v[32:33], v5, off
